# prompt diff-attention epilogue: 16 dwordx2 row-per-lane stores -> 8 dwordx4 via v_permlane32_swap
# speedup vs baseline: 1.0314x; 1.0012x over previous
; #define LAS __attribute__((address_space(3)))
; __device__ __forceinline__ float frcp(float x) { return __builtin_amdgcn_rcpf(x); }
;     ...
;         const float inv = frcp(l);
;         LAS float* X = (LAS float*)L + sub * 4096;
;         if (map == 1) {
; #pragma unroll
;             for (int eb = 0; eb < 4; ++eb)
; #pragma unroll
;                 for (int rg = 0; rg < 16; ++rg) X[(eb * 32 + (rg & 3) + 8 * (rg >> 2) + 4 * hi) * 32 + r] = OT[eb][rg] * inv;
;         }
;         __syncthreads();
;         if (map == 0) {
;             float ss = 0.f;
; #pragma unroll
;             for (int eb = 0; eb < 4; ++eb)
; #pragma unroll
;                 for (int rg = 0; rg < 16; ++rg) { const float o = OT[eb][rg] * inv - lam * X[(eb * 32 + (rg & 3) + 8 * (rg >> 2) + 4 * hi) * 32 + r]; OT[eb][rg] = o; ss += o * o; }
;             ss += __shfl_xor(ss, 32);
.LBB0_941:
	s_cmpk_gt_u32 s8, 0xff
	s_waitcnt lgkmcnt(0)
	s_barrier
	s_cbranch_scc1 .LBB0_943
	v_add_u32_e32 v67, 0x400, v66
	ds_read2_b32 v[70:71], v66 offset1:32
	ds_read2_b32 v[72:73], v66 offset0:64 offset1:96
	ds_read2_b32 v[74:75], v67 offset1:32
	ds_read2_b32 v[76:77], v67 offset0:64 offset1:96
	v_add_u32_e32 v67, 0x800, v66
	ds_read2_b32 v[84:85], v67 offset1:32
	ds_read2_b32 v[86:87], v67 offset0:64 offset1:96
	v_add_u32_e32 v67, 0xc00, v66
	ds_read2_b32 v[88:89], v67 offset1:32
	ds_read2_b32 v[90:91], v67 offset0:64 offset1:96
	v_add_u32_e32 v67, 0x1000, v66
	ds_read2_b32 v[92:93], v67 offset1:32
	ds_read2_b32 v[94:95], v67 offset0:64 offset1:96
	v_add_u32_e32 v67, 0x1400, v66
	ds_read2_b32 v[96:97], v67 offset1:32
	ds_read2_b32 v[98:99], v67 offset0:64 offset1:96
	v_add_u32_e32 v67, 0x1800, v66
	s_waitcnt lgkmcnt(11)
	v_pk_mul_f32 v[70:71], v[160:161], v[70:71]
	ds_read2_b32 v[100:101], v67 offset1:32
	ds_read2_b32 v[102:103], v67 offset0:64 offset1:96
	v_add_u32_e32 v67, 0x1c00, v66
	v_pk_fma_f32 v[70:71], v[50:51], v[0:1], v[70:71] op_sel_hi:[1,0,1] neg_lo:[0,0,1] neg_hi:[0,0,1]
	s_waitcnt lgkmcnt(10)
	v_pk_mul_f32 v[50:51], v[160:161], v[76:77]
	ds_read2_b32 v[104:105], v67 offset1:32
	ds_read2_b32 v[106:107], v67 offset0:64 offset1:96
	v_add_u32_e32 v67, 0x2000, v66
	v_pk_mul_f32 v[72:73], v[160:161], v[72:73]
	v_pk_fma_f32 v[50:51], v[56:57], v[0:1], v[50:51] op_sel_hi:[1,0,1] neg_lo:[0,0,1] neg_hi:[0,0,1]
	v_pk_mul_f32 v[56:57], v[160:161], v[74:75]
	ds_read2_b32 v[108:109], v67 offset1:32
	ds_read2_b32 v[110:111], v67 offset0:64 offset1:96
	v_add_u32_e32 v67, 0x2400, v66
	v_pk_fma_f32 v[52:53], v[52:53], v[0:1], v[72:73] op_sel_hi:[1,0,1] neg_lo:[0,0,1] neg_hi:[0,0,1]
	v_pk_fma_f32 v[72:73], v[54:55], v[0:1], v[56:57] op_sel_hi:[1,0,1] neg_lo:[0,0,1] neg_hi:[0,0,1]
	s_waitcnt lgkmcnt(13)
	v_pk_mul_f32 v[56:57], v[160:161], v[84:85]
	ds_read2_b32 v[112:113], v67 offset1:32
	s_waitcnt vmcnt(3)
	ds_read2_b32 v[114:115], v67 offset0:64 offset1:96
	v_add_u32_e32 v67, 0x2800, v66
	v_pk_fma_f32 v[74:75], v[58:59], v[0:1], v[56:57] op_sel_hi:[1,0,1] neg_lo:[0,0,1] neg_hi:[0,0,1]
	s_waitcnt lgkmcnt(13)
	v_pk_mul_f32 v[58:59], v[160:161], v[88:89]
	ds_read2_b32 v[116:117], v67 offset1:32
	s_waitcnt vmcnt(2)
	ds_read2_b32 v[118:119], v67 offset0:64 offset1:96
	v_add_u32_e32 v67, 0x2c00, v66
	v_pk_fma_f32 v[76:77], v[62:63], v[0:1], v[58:59] op_sel_hi:[1,0,1] neg_lo:[0,0,1] neg_hi:[0,0,1]
	s_waitcnt lgkmcnt(12)
	v_pk_mul_f32 v[58:59], v[160:161], v[94:95]
	ds_read2_b32 v[120:121], v67 offset1:32
	s_waitcnt vmcnt(1)
	ds_read2_b32 v[122:123], v67 offset0:64 offset1:96
	v_add_u32_e32 v67, 0x3000, v66
	v_pk_mul_f32 v[54:55], v[160:161], v[86:87]
	v_pk_fma_f32 v[58:59], v[36:37], v[0:1], v[58:59] op_sel_hi:[1,0,1] neg_lo:[0,0,1] neg_hi:[0,0,1]
	v_pk_mul_f32 v[36:37], v[160:161], v[92:93]
	ds_read2_b32 v[124:125], v67 offset1:32
	s_waitcnt vmcnt(0)
	ds_read2_b32 v[126:127], v67 offset0:64 offset1:96
	v_add_u32_e32 v67, 0x3400, v66
	v_add_u32_e32 v78, 0x3800, v66
	v_pk_fma_f32 v[54:55], v[60:61], v[0:1], v[54:55] op_sel_hi:[1,0,1] neg_lo:[0,0,1] neg_hi:[0,0,1]
	v_pk_fma_f32 v[60:61], v[34:35], v[0:1], v[36:37] op_sel_hi:[1,0,1] neg_lo:[0,0,1] neg_hi:[0,0,1]
	s_waitcnt lgkmcnt(14)
	v_pk_mul_f32 v[34:35], v[160:161], v[98:99]
	ds_read2_b32 v[128:129], v67 offset1:32
	ds_read2_b32 v[68:69], v78 offset0:64 offset1:96
	ds_read2_b32 v[130:131], v67 offset0:64 offset1:96
	ds_read2_b32 v[132:133], v78 offset1:32
	v_pk_fma_f32 v[34:35], v[40:41], v[0:1], v[34:35] op_sel_hi:[1,0,1] neg_lo:[0,0,1] neg_hi:[0,0,1]
	s_waitcnt lgkmcnt(14)
	v_pk_mul_f32 v[40:41], v[160:161], v[104:105]
	v_pk_mul_f32 v[36:37], v[160:161], v[96:97]
	v_pk_fma_f32 v[46:47], v[46:47], v[0:1], v[40:41] op_sel_hi:[1,0,1] neg_lo:[0,0,1] neg_hi:[0,0,1]
	s_waitcnt lgkmcnt(12)
	v_pk_mul_f32 v[40:41], v[160:161], v[110:111]
	v_pk_mul_f32 v[56:57], v[160:161], v[90:91]
	v_pk_fma_f32 v[62:63], v[38:39], v[0:1], v[36:37] op_sel_hi:[1,0,1] neg_lo:[0,0,1] neg_hi:[0,0,1]
	v_pk_mul_f32 v[38:39], v[160:161], v[100:101]
	v_pk_fma_f32 v[40:41], v[20:21], v[0:1], v[40:41] op_sel_hi:[1,0,1] neg_lo:[0,0,1] neg_hi:[0,0,1]
	v_pk_mul_f32 v[20:21], v[160:161], v[108:109]
	v_add_u32_e32 v78, 0x3c00, v66
	s_waitcnt lgkmcnt(2)
	v_pk_mul_f32 v[66:67], v[160:161], v[68:69]
	v_pk_fma_f32 v[56:57], v[64:65], v[0:1], v[56:57] op_sel_hi:[1,0,1] neg_lo:[0,0,1] neg_hi:[0,0,1]
	v_pk_mul_f32 v[36:37], v[160:161], v[102:103]
	v_pk_fma_f32 v[64:65], v[42:43], v[0:1], v[38:39] op_sel_hi:[1,0,1] neg_lo:[0,0,1] neg_hi:[0,0,1]
	v_pk_fma_f32 v[42:43], v[18:19], v[0:1], v[20:21] op_sel_hi:[1,0,1] neg_lo:[0,0,1] neg_hi:[0,0,1]
	v_pk_mul_f32 v[18:19], v[160:161], v[114:115]
	v_pk_mul_f32 v[20:21], v[160:161], v[112:113]
	ds_read2_b32 v[80:81], v78 offset1:32
	v_pk_fma_f32 v[66:67], v[12:13], v[0:1], v[66:67] op_sel_hi:[1,0,1] neg_lo:[0,0,1] neg_hi:[0,0,1]
	ds_read2_b32 v[12:13], v78 offset0:64 offset1:96
	v_pk_fma_f32 v[36:37], v[44:45], v[0:1], v[36:37] op_sel_hi:[1,0,1] neg_lo:[0,0,1] neg_hi:[0,0,1]
	v_pk_fma_f32 v[18:19], v[24:25], v[0:1], v[18:19] op_sel_hi:[1,0,1] neg_lo:[0,0,1] neg_hi:[0,0,1]
	v_pk_fma_f32 v[44:45], v[22:23], v[0:1], v[20:21] op_sel_hi:[1,0,1] neg_lo:[0,0,1] neg_hi:[0,0,1]
	v_pk_mul_f32 v[20:21], v[160:161], v[118:119]
	v_pk_mul_f32 v[24:25], v[160:161], v[120:121]
	v_pk_fma_f32 v[20:21], v[28:29], v[0:1], v[20:21] op_sel_hi:[1,0,1] neg_lo:[0,0,1] neg_hi:[0,0,1]
	v_pk_fma_f32 v[28:29], v[30:31], v[0:1], v[24:25] op_sel_hi:[1,0,1] neg_lo:[0,0,1] neg_hi:[0,0,1]
	v_pk_mul_f32 v[24:25], v[160:161], v[126:127]
	v_pk_mul_f32 v[22:23], v[160:161], v[116:117]
	v_pk_fma_f32 v[4:5], v[4:5], v[0:1], v[24:25] op_sel_hi:[1,0,1] neg_lo:[0,0,1] neg_hi:[0,0,1]
	v_pk_mul_f32 v[24:25], v[160:161], v[124:125]
	s_waitcnt lgkmcnt(1)
; #define GASP __attribute__((address_space(1)))
;     ...
;             float ss = 0.f;
; #pragma unroll
;             for (int eb = 0; eb < 4; ++eb)
; #pragma unroll
;                 for (int rg = 0; rg < 16; ++rg) { const float o = OT[eb][rg] * inv - lam * X[(eb * 32 + (rg & 3) + 8 * (rg >> 2) + 4 * hi) * 32 + r]; OT[eb][rg] = o; ss += o * o; }
;             ss += __shfl_xor(ss, 32);
;             const float rms = 0.8f / sqrtf(ss * (1.f / 128.f) + LN_EPS);
;             const float* sg = p.in[16];
;             bf16_t* op = (bf16_t*)(ws + O_MIX) + (size_t)(rowq0 + r) * D + h * 128 + 4 * hi;
; #pragma unroll
;             for (int eb = 0; eb < 4; ++eb)
; #pragma unroll
;                 for (int g4 = 0; g4 < 4; ++g4) { const int e0 = eb * 32 + 8 * g4; const f32x4 gv = *(const GASP f32x4*)(sg + e0 + 4 * hi);
	v_pk_mul_f32 v[68:69], v[160:161], v[80:81]
	v_pk_fma_f32 v[24:25], v[2:3], v[0:1], v[24:25] op_sel_hi:[1,0,1] neg_lo:[0,0,1] neg_hi:[0,0,1]
	v_pk_mul_f32 v[2:3], v[160:161], v[130:131]
	s_waitcnt lgkmcnt(0)
	v_pk_mul_f32 v[12:13], v[160:161], v[12:13]
	v_pk_fma_f32 v[2:3], v[8:9], v[0:1], v[2:3] op_sel_hi:[1,0,1] neg_lo:[0,0,1] neg_hi:[0,0,1]
	v_pk_mul_f32 v[8:9], v[160:161], v[128:129]
	v_pk_mul_f32 v[136:137], v[70:71], v[70:71]
	v_pk_mul_f32 v[38:39], v[160:161], v[106:107]
	v_pk_fma_f32 v[26:27], v[26:27], v[0:1], v[22:23] op_sel_hi:[1,0,1] neg_lo:[0,0,1] neg_hi:[0,0,1]
	v_pk_mul_f32 v[22:23], v[160:161], v[122:123]
	v_pk_fma_f32 v[8:9], v[6:7], v[0:1], v[8:9] op_sel_hi:[1,0,1] neg_lo:[0,0,1] neg_hi:[0,0,1]
	v_pk_mul_f32 v[6:7], v[160:161], v[132:133]
	v_pk_fma_f32 v[68:69], v[14:15], v[0:1], v[68:69] op_sel_hi:[1,0,1] neg_lo:[0,0,1] neg_hi:[0,0,1]
	v_pk_fma_f32 v[16:17], v[16:17], v[0:1], v[12:13] op_sel_hi:[1,0,1] neg_lo:[0,0,1] neg_hi:[0,0,1]
	v_pk_mul_f32 v[134:135], v[52:53], v[52:53]
	v_pk_fma_f32 v[38:39], v[48:49], v[0:1], v[38:39] op_sel_hi:[1,0,1] neg_lo:[0,0,1] neg_hi:[0,0,1]
	v_pk_fma_f32 v[22:23], v[32:33], v[0:1], v[22:23] op_sel_hi:[1,0,1] neg_lo:[0,0,1] neg_hi:[0,0,1]
	v_pk_fma_f32 v[6:7], v[10:11], v[0:1], v[6:7] op_sel_hi:[1,0,1] neg_lo:[0,0,1] neg_hi:[0,0,1]
	v_add_f32_e32 v0, v136, v137
	v_add_f32_e32 v0, v0, v134
	v_pk_mul_f32 v[140:141], v[72:73], v[72:73]
	v_add_f32_e32 v0, v0, v135
	v_add_f32_e32 v0, v0, v140
	v_pk_mul_f32 v[138:139], v[50:51], v[50:51]
	v_add_f32_e32 v0, v0, v141
	v_add_f32_e32 v0, v0, v138
	v_pk_mul_f32 v[84:85], v[74:75], v[74:75]
	v_add_f32_e32 v0, v0, v139
	v_add_f32_e32 v0, v0, v84
	v_pk_mul_f32 v[86:87], v[54:55], v[54:55]
	v_add_f32_e32 v0, v0, v85
	v_add_f32_e32 v0, v0, v86
	v_pk_mul_f32 v[88:89], v[76:77], v[76:77]
	v_add_f32_e32 v0, v0, v87
	v_add_f32_e32 v0, v0, v88
	v_pk_mul_f32 v[90:91], v[56:57], v[56:57]
	v_add_f32_e32 v0, v0, v89
	v_add_f32_e32 v0, v0, v90
	v_pk_mul_f32 v[92:93], v[60:61], v[60:61]
	v_add_f32_e32 v0, v0, v91
	v_add_f32_e32 v0, v0, v92
	v_pk_mul_f32 v[94:95], v[58:59], v[58:59]
	v_add_f32_e32 v0, v0, v93
	v_add_f32_e32 v0, v0, v94
	v_lshlrev_b32_e32 v142, 2, v147
	v_pk_mul_f32 v[96:97], v[62:63], v[62:63]
	v_add_f32_e32 v0, v0, v95
	global_load_dwordx4 v[12:15], v142, s[16:17]
	v_add_f32_e32 v0, v0, v96
	v_pk_mul_f32 v[98:99], v[34:35], v[34:35]
	v_add_f32_e32 v0, v0, v97
	v_add_f32_e32 v0, v0, v98
	v_pk_mul_f32 v[100:101], v[64:65], v[64:65]
	v_add_f32_e32 v0, v0, v99
	v_add_f32_e32 v0, v0, v100
	v_pk_mul_f32 v[102:103], v[36:37], v[36:37]
	v_add_f32_e32 v0, v0, v101
	v_add_f32_e32 v0, v0, v102
	v_pk_mul_f32 v[104:105], v[46:47], v[46:47]
	v_add_f32_e32 v0, v0, v103
	v_add_f32_e32 v0, v0, v104
	v_pk_mul_f32 v[48:49], v[38:39], v[38:39]
	v_add_f32_e32 v0, v0, v105
	v_add_f32_e32 v0, v0, v48
	v_pk_mul_f32 v[108:109], v[42:43], v[42:43]
	v_add_f32_e32 v0, v0, v49
	v_add_f32_e32 v0, v0, v108
	v_pk_mul_f32 v[106:107], v[40:41], v[40:41]
	v_add_f32_e32 v0, v0, v109
	v_add_f32_e32 v0, v0, v106
	v_pk_mul_f32 v[112:113], v[44:45], v[44:45]
	v_add_f32_e32 v0, v0, v107
	v_add_f32_e32 v0, v0, v112
	v_pk_mul_f32 v[110:111], v[18:19], v[18:19]
	v_add_f32_e32 v0, v0, v113
	v_add_f32_e32 v0, v0, v110
	v_pk_mul_f32 v[116:117], v[26:27], v[26:27]
	v_add_f32_e32 v0, v0, v111
	v_add_f32_e32 v0, v0, v116
	v_pk_mul_f32 v[114:115], v[20:21], v[20:21]
	v_add_f32_e32 v0, v0, v117
	v_add_f32_e32 v0, v0, v114
	v_pk_mul_f32 v[30:31], v[28:29], v[28:29]
	v_add_f32_e32 v0, v0, v115
	v_add_f32_e32 v0, v0, v30
	v_pk_mul_f32 v[32:33], v[22:23], v[22:23]
	v_add_f32_e32 v0, v0, v31
	v_add_f32_e32 v0, v0, v32
	v_pk_mul_f32 v[120:121], v[24:25], v[24:25]
	v_add_f32_e32 v0, v0, v33
	v_add_f32_e32 v0, v0, v120
	v_pk_mul_f32 v[118:119], v[4:5], v[4:5]
	v_add_f32_e32 v0, v0, v121
	v_add_f32_e32 v0, v0, v118
	v_pk_mul_f32 v[124:125], v[8:9], v[8:9]
	v_add_f32_e32 v0, v0, v119
	v_add_f32_e32 v0, v0, v124
	v_pk_mul_f32 v[122:123], v[2:3], v[2:3]
	v_add_f32_e32 v0, v0, v125
	v_add_f32_e32 v0, v0, v122
	v_pk_mul_f32 v[10:11], v[6:7], v[6:7]
	v_add_f32_e32 v0, v0, v123
	v_add_f32_e32 v0, v0, v10
	v_pk_mul_f32 v[78:79], v[66:67], v[66:67]
	v_add_f32_e32 v0, v0, v11
	v_add_f32_e32 v0, v0, v78
	v_pk_mul_f32 v[80:81], v[68:69], v[68:69]
	v_add_f32_e32 v0, v0, v79
	v_add_f32_e32 v0, v0, v80
	v_pk_mul_f32 v[82:83], v[16:17], v[16:17]
	v_add_f32_e32 v0, v0, v81
	v_add_f32_e32 v0, v0, v82
	v_add_f32_e32 v0, v0, v83
	ds_bpermute_b32 v10, v171, v0
	global_load_dwordx4 v[80:83], v142, s[16:17] offset:32
	global_load_dwordx4 v[84:87], v142, s[16:17] offset:64
	global_load_dwordx4 v[88:91], v142, s[16:17] offset:96
	global_load_dwordx4 v[92:95], v142, s[16:17] offset:128
	global_load_dwordx4 v[96:99], v142, s[16:17] offset:160
	global_load_dwordx4 v[100:103], v142, s[16:17] offset:192
	global_load_dwordx4 v[104:107], v142, s[16:17] offset:224
	global_load_dwordx4 v[108:111], v142, s[16:17] offset:256
	global_load_dwordx4 v[112:115], v142, s[16:17] offset:288
	global_load_dwordx4 v[116:119], v142, s[16:17] offset:320
	global_load_dwordx4 v[120:123], v142, s[16:17] offset:352
	global_load_dwordx4 v[124:127], v142, s[16:17] offset:384
	global_load_dwordx4 v[128:131], v142, s[16:17] offset:416
	global_load_dwordx4 v[132:135], v142, s[16:17] offset:448
	global_load_dwordx4 v[136:139], v142, s[16:17] offset:480
	s_lshl_b32 s30, s5, 1
	s_waitcnt lgkmcnt(0)
;     ...
;             ss += __shfl_xor(ss, 32);
;             const float rms = 0.8f / sqrtf(ss * (1.f / 128.f) + LN_EPS);
;             const float* sg = p.in[16];
;             bf16_t* op = (bf16_t*)(ws + O_MIX) + (size_t)(rowq0 + r) * D + h * 128 + 4 * hi;
	v_add_f32_e32 v0, v0, v10
	v_fmamk_f32 v0, v0, 0x3c000000, v172
	v_mul_f32_e32 v10, 0x4f800000, v0
	v_cmp_gt_f32_e32 vcc, s35, v0
	s_nop 1
	v_cndmask_b32_e32 v30, v0, v10, vcc
	v_sqrt_f32_e32 v31, v30
	v_lshlrev_b32_e32 v0, 11, v146
	v_lshl_add_u64 v[10:11], s[76:77], 0, v[0:1]
	v_lshl_add_u64 v[10:11], v[10:11], 0, s[30:31]
	v_add_u32_e32 v0, -1, v31
	v_fma_f32 v32, -v0, v31, v30
	v_cmp_ge_f32_e64 s[6:7], 0, v32
	v_add_u32_e32 v32, 1, v31
	s_nop 0
	v_cndmask_b32_e64 v0, v31, v0, s[6:7]
	v_fma_f32 v31, -v32, v31, v30
	v_cmp_lt_f32_e64 s[6:7], 0, v31
	s_nop 1
	v_cndmask_b32_e64 v0, v0, v32, s[6:7]
	v_mul_f32_e32 v31, 0x37800000, v0
	v_cndmask_b32_e32 v0, v0, v31, vcc
	v_cmp_class_f32_e32 vcc, v30, v170
	s_nop 1
	v_cndmask_b32_e32 v32, v0, v30, vcc
	v_div_scale_f32 v33, s[6:7], v32, v32, s1
	v_rcp_f32_e32 v48, v33
	v_lshlrev_b32_e32 v0, 1, v147
	v_lshl_add_u64 v[30:31], v[10:11], 0, v[0:1]
	v_fma_f32 v0, -v33, v48, 1.0
	v_fmac_f32_e32 v48, v0, v48
	v_div_scale_f32 v0, vcc, s1, v32, s1
	v_mul_f32_e32 v10, v0, v48
	v_fma_f32 v11, -v33, v10, v0
	v_fmac_f32_e32 v10, v11, v48
	v_fma_f32 v0, -v33, v10, v0
	v_div_fmas_f32 v0, v0, v48, v10
	v_div_fixup_f32 v0, v0, v32, s1
	s_waitcnt vmcnt(0)
; #define GASP __attribute__((address_space(1)))
;     ...
;             bf16_t* op = (bf16_t*)(ws + O_MIX) + (size_t)(rowq0 + r) * D + h * 128 + 4 * hi;
; #pragma unroll
;             for (int eb = 0; eb < 4; ++eb)
; #pragma unroll
;                 for (int g4 = 0; g4 < 4; ++g4) { const int e0 = eb * 32 + 8 * g4; const f32x4 gv = *(const GASP f32x4*)(sg + e0 + 4 * hi);
;                     u32x2 w; w.x = pk2(OT[eb][4 * g4] * rms * gv[0], OT[eb][4 * g4 + 1] * rms * gv[1]); w.y = pk2(OT[eb][4 * g4 + 2] * rms * gv[2], OT[eb][4 * g4 + 3] * rms * gv[3]);
;                     *(GASP u32x2*)(op + e0) = w; }
;         }
	v_lshlrev_b32_e32 v202, 1, v147
	v_mov_b32_e32 v203, 0
	v_lshl_add_u64 v[206:207], v[30:31], 0, v[202:203]
	v_pk_mul_f32 v[202:203], v[70:71], v[0:1] op_sel_hi:[1,0]
	v_pk_mul_f32 v[204:205], v[52:53], v[0:1] op_sel_hi:[1,0]
	v_pk_mul_f32 v[202:203], v[12:13], v[202:203]
	v_pk_mul_f32 v[204:205], v[14:15], v[204:205]
	s_nop 0
	v_cvt_pk_bf16_f32 v194, v202, v203
	v_cvt_pk_bf16_f32 v195, v204, v205
	v_pk_mul_f32 v[202:203], v[72:73], v[0:1] op_sel_hi:[1,0]
	v_pk_mul_f32 v[204:205], v[50:51], v[0:1] op_sel_hi:[1,0]
	v_pk_mul_f32 v[202:203], v[80:81], v[202:203]
	v_pk_mul_f32 v[204:205], v[82:83], v[204:205]
	s_nop 0
	v_cvt_pk_bf16_f32 v196, v202, v203
	v_cvt_pk_bf16_f32 v197, v204, v205
	s_nop 1
	v_permlane32_swap_b32_e32 v194, v196
	v_permlane32_swap_b32_e32 v195, v197
	global_store_dwordx4 v[206:207], v[194:197], off
	v_pk_mul_f32 v[202:203], v[74:75], v[0:1] op_sel_hi:[1,0]
	v_pk_mul_f32 v[204:205], v[54:55], v[0:1] op_sel_hi:[1,0]
	v_pk_mul_f32 v[202:203], v[84:85], v[202:203]
	v_pk_mul_f32 v[204:205], v[86:87], v[204:205]
	s_nop 0
	v_cvt_pk_bf16_f32 v198, v202, v203
	v_cvt_pk_bf16_f32 v199, v204, v205
	v_pk_mul_f32 v[202:203], v[76:77], v[0:1] op_sel_hi:[1,0]
	v_pk_mul_f32 v[204:205], v[56:57], v[0:1] op_sel_hi:[1,0]
	v_pk_mul_f32 v[202:203], v[88:89], v[202:203]
	v_pk_mul_f32 v[204:205], v[90:91], v[204:205]
	s_nop 0
	v_cvt_pk_bf16_f32 v200, v202, v203
	v_cvt_pk_bf16_f32 v201, v204, v205
	s_nop 1
	v_permlane32_swap_b32_e32 v198, v200
	v_permlane32_swap_b32_e32 v199, v201
	global_store_dwordx4 v[206:207], v[198:201], off offset:32
	v_pk_mul_f32 v[202:203], v[60:61], v[0:1] op_sel_hi:[1,0]
	v_pk_mul_f32 v[204:205], v[58:59], v[0:1] op_sel_hi:[1,0]
	v_pk_mul_f32 v[202:203], v[92:93], v[202:203]
	v_pk_mul_f32 v[204:205], v[94:95], v[204:205]
	s_nop 0
	v_cvt_pk_bf16_f32 v194, v202, v203
	v_cvt_pk_bf16_f32 v195, v204, v205
	v_pk_mul_f32 v[202:203], v[62:63], v[0:1] op_sel_hi:[1,0]
	v_pk_mul_f32 v[204:205], v[34:35], v[0:1] op_sel_hi:[1,0]
	v_pk_mul_f32 v[202:203], v[96:97], v[202:203]
	v_pk_mul_f32 v[204:205], v[98:99], v[204:205]
	s_nop 0
	v_cvt_pk_bf16_f32 v196, v202, v203
	v_cvt_pk_bf16_f32 v197, v204, v205
	s_nop 1
	v_permlane32_swap_b32_e32 v194, v196
	v_permlane32_swap_b32_e32 v195, v197
	global_store_dwordx4 v[206:207], v[194:197], off offset:64
	v_pk_mul_f32 v[202:203], v[64:65], v[0:1] op_sel_hi:[1,0]
	v_pk_mul_f32 v[204:205], v[36:37], v[0:1] op_sel_hi:[1,0]
	v_pk_mul_f32 v[202:203], v[100:101], v[202:203]
	v_pk_mul_f32 v[204:205], v[102:103], v[204:205]
	s_nop 0
	v_cvt_pk_bf16_f32 v198, v202, v203
	v_cvt_pk_bf16_f32 v199, v204, v205
	v_pk_mul_f32 v[202:203], v[46:47], v[0:1] op_sel_hi:[1,0]
	v_pk_mul_f32 v[204:205], v[38:39], v[0:1] op_sel_hi:[1,0]
	v_pk_mul_f32 v[202:203], v[104:105], v[202:203]
	v_pk_mul_f32 v[204:205], v[106:107], v[204:205]
	s_nop 0
	v_cvt_pk_bf16_f32 v200, v202, v203
	v_cvt_pk_bf16_f32 v201, v204, v205
	s_nop 1
	v_permlane32_swap_b32_e32 v198, v200
	v_permlane32_swap_b32_e32 v199, v201
	global_store_dwordx4 v[206:207], v[198:201], off offset:96
	v_pk_mul_f32 v[202:203], v[42:43], v[0:1] op_sel_hi:[1,0]
	v_pk_mul_f32 v[204:205], v[40:41], v[0:1] op_sel_hi:[1,0]
	v_pk_mul_f32 v[202:203], v[108:109], v[202:203]
	v_pk_mul_f32 v[204:205], v[110:111], v[204:205]
	s_nop 0
	v_cvt_pk_bf16_f32 v194, v202, v203
	v_cvt_pk_bf16_f32 v195, v204, v205
	v_pk_mul_f32 v[202:203], v[44:45], v[0:1] op_sel_hi:[1,0]
	v_pk_mul_f32 v[204:205], v[18:19], v[0:1] op_sel_hi:[1,0]
	v_pk_mul_f32 v[202:203], v[112:113], v[202:203]
	v_pk_mul_f32 v[204:205], v[114:115], v[204:205]
	s_nop 0
	v_cvt_pk_bf16_f32 v196, v202, v203
	v_cvt_pk_bf16_f32 v197, v204, v205
	s_nop 1
	v_permlane32_swap_b32_e32 v194, v196
	v_permlane32_swap_b32_e32 v195, v197
	global_store_dwordx4 v[206:207], v[194:197], off offset:128
	v_pk_mul_f32 v[202:203], v[26:27], v[0:1] op_sel_hi:[1,0]
	v_pk_mul_f32 v[204:205], v[20:21], v[0:1] op_sel_hi:[1,0]
	v_pk_mul_f32 v[202:203], v[116:117], v[202:203]
	v_pk_mul_f32 v[204:205], v[118:119], v[204:205]
	s_nop 0
	v_cvt_pk_bf16_f32 v198, v202, v203
	v_cvt_pk_bf16_f32 v199, v204, v205
	v_pk_mul_f32 v[202:203], v[28:29], v[0:1] op_sel_hi:[1,0]
	v_pk_mul_f32 v[204:205], v[22:23], v[0:1] op_sel_hi:[1,0]
	v_pk_mul_f32 v[202:203], v[120:121], v[202:203]
	v_pk_mul_f32 v[204:205], v[122:123], v[204:205]
	s_nop 0
	v_cvt_pk_bf16_f32 v200, v202, v203
	v_cvt_pk_bf16_f32 v201, v204, v205
	s_nop 1
	v_permlane32_swap_b32_e32 v198, v200
	v_permlane32_swap_b32_e32 v199, v201
	global_store_dwordx4 v[206:207], v[198:201], off offset:160
	v_pk_mul_f32 v[202:203], v[24:25], v[0:1] op_sel_hi:[1,0]
	v_pk_mul_f32 v[204:205], v[4:5], v[0:1] op_sel_hi:[1,0]
	v_pk_mul_f32 v[202:203], v[124:125], v[202:203]
	v_pk_mul_f32 v[204:205], v[126:127], v[204:205]
	s_nop 0
	v_cvt_pk_bf16_f32 v194, v202, v203
	v_cvt_pk_bf16_f32 v195, v204, v205
	v_pk_mul_f32 v[202:203], v[8:9], v[0:1] op_sel_hi:[1,0]
	v_pk_mul_f32 v[204:205], v[2:3], v[0:1] op_sel_hi:[1,0]
	v_pk_mul_f32 v[202:203], v[128:129], v[202:203]
	v_pk_mul_f32 v[204:205], v[130:131], v[204:205]
	s_nop 0
	v_cvt_pk_bf16_f32 v196, v202, v203
	v_cvt_pk_bf16_f32 v197, v204, v205
	s_nop 1
	v_permlane32_swap_b32_e32 v194, v196
	v_permlane32_swap_b32_e32 v195, v197
	global_store_dwordx4 v[206:207], v[194:197], off offset:192
	v_pk_mul_f32 v[202:203], v[6:7], v[0:1] op_sel_hi:[1,0]
	v_pk_mul_f32 v[204:205], v[66:67], v[0:1] op_sel_hi:[1,0]
	v_pk_mul_f32 v[202:203], v[132:133], v[202:203]
	v_pk_mul_f32 v[204:205], v[134:135], v[204:205]
	s_nop 0
	v_cvt_pk_bf16_f32 v198, v202, v203
	v_cvt_pk_bf16_f32 v199, v204, v205
	v_pk_mul_f32 v[202:203], v[68:69], v[0:1] op_sel_hi:[1,0]
	v_pk_mul_f32 v[204:205], v[16:17], v[0:1] op_sel_hi:[1,0]
	v_pk_mul_f32 v[202:203], v[136:137], v[202:203]
	v_pk_mul_f32 v[204:205], v[138:139], v[204:205]
	s_nop 0
	v_cvt_pk_bf16_f32 v200, v202, v203
	v_cvt_pk_bf16_f32 v201, v204, v205
	s_nop 1
	v_permlane32_swap_b32_e32 v198, v200
	v_permlane32_swap_b32_e32 v199, v201
	global_store_dwordx4 v[206:207], v[198:201], off offset:224
